# FFN down epilogues (P2/P10) rewritten by hand (packed fma, permlane reduction, hoisted loads, running pointers); unreachable compiled bodies removed
# speedup vs baseline: 1.0027x; 1.0027x over previous
.LBB0_196:
	v_ashrrev_i32_e32 v142, 2, v192
	v_and_b32_e32 v142, 0xffffffc0, v142
	s_lshl_b32 vcc_lo, s73, 8
	v_and_or_b32 v143, v192, 15, vcc_lo
	v_add_u32_e32 v142, v143, v142
	v_ashrrev_i32_e32 v143, 31, v142
	v_bfe_u32 v147, v192, 4, 2
	v_lshrrev_b32_e32 v80, 1, v192
	v_and_b32_e32 v80, 0x60, v80
	s_lshl_b32 vcc_lo, s72, 8
	v_add_u32_e32 v80, vcc_lo, v80
	v_lshl_add_u32 v80, v147, 3, v80
	v_lshlrev_b32_e32 v80, 1, v80
	v_lshlrev_b64 v[164:165], 11, v[142:143]
	v_lshl_add_u64 v[164:165], s[38:39], 0, v[164:165]
	v_lshl_add_u64 v[164:165], v[164:165], 0, v[80:81]
	v_mov_b32_e32 v248, v164
	v_mov_b32_e32 v249, v165
	global_load_dwordx4 v[148:151], v[248:249], off
	global_load_dwordx4 v[160:163], v[248:249], off offset:256
	s_mov_b64 vcc, 0x8000
	s_nop 0
	v_lshl_add_u64 v[248:249], v[248:249], 0, vcc
	global_load_dwordx4 v[176:179], v[248:249], off
	global_load_dwordx4 v[180:183], v[248:249], off offset:256
	s_mov_b64 vcc, 0x8000
	s_nop 0
	v_lshl_add_u64 v[248:249], v[248:249], 0, vcc
	global_load_dwordx4 v[184:187], v[248:249], off
	global_load_dwordx4 v[188:191], v[248:249], off offset:256
	s_mov_b64 vcc, 0x8000
	s_nop 0
	v_lshl_add_u64 v[248:249], v[248:249], 0, vcc
	global_load_dwordx4 v[204:207], v[248:249], off
	global_load_dwordx4 v[208:211], v[248:249], off offset:256
	s_mov_b64 vcc, 0x28000
	s_nop 0
	v_lshl_add_u64 v[248:249], v[248:249], 0, vcc
	global_load_dwordx4 v[212:215], v[248:249], off
	global_load_dwordx4 v[216:219], v[248:249], off offset:256
	s_mov_b64 vcc, 0x8000
	s_nop 0
	v_lshl_add_u64 v[248:249], v[248:249], 0, vcc
	global_load_dwordx4 v[220:223], v[248:249], off
	global_load_dwordx4 v[224:227], v[248:249], off offset:256
	s_mov_b64 vcc, 0x8000
	s_nop 0
	v_lshl_add_u64 v[248:249], v[248:249], 0, vcc
	global_load_dwordx4 v[228:231], v[248:249], off
	global_load_dwordx4 v[232:235], v[248:249], off offset:256
	s_mov_b64 vcc, 0x8000
	s_nop 0
	v_lshl_add_u64 v[248:249], v[248:249], 0, vcc
	global_load_dwordx4 v[236:239], v[248:249], off
	global_load_dwordx4 v[240:243], v[248:249], off offset:256
	v_readlane_b32 s54, v253, 14
	v_readlane_b32 s55, v253, 15
	v_cmp_eq_u32_e64 s[46:47], 0, v147
	s_nop 0
	v_lshl_add_u64 v[166:167], v[142:143], 2, s[54:55]
	s_waitcnt vmcnt(15)
	v_lshlrev_b32_e32 v168, 16, v148
	v_and_b32_e32 v169, 0xffff0000, v148
	v_lshlrev_b32_e32 v170, 16, v149
	v_and_b32_e32 v171, 0xffff0000, v149
	v_lshlrev_b32_e32 v172, 16, v150
	v_and_b32_e32 v173, 0xffff0000, v150
	v_lshlrev_b32_e32 v174, 16, v151
	v_and_b32_e32 v175, 0xffff0000, v151
	v_pk_fma_f32 v[168:169], v[126:127], 0.5, v[168:169] op_sel_hi:[1,0,1]
	v_pk_fma_f32 v[170:171], v[128:129], 0.5, v[170:171] op_sel_hi:[1,0,1]
	v_pk_fma_f32 v[172:173], v[122:123], 0.5, v[172:173] op_sel_hi:[1,0,1]
	v_pk_fma_f32 v[174:175], v[124:125], 0.5, v[174:175] op_sel_hi:[1,0,1]
	v_pk_mul_f32 v[244:245], v[168:169], v[168:169]
	v_pk_fma_f32 v[244:245], v[170:171], v[170:171], v[244:245]
	v_pk_fma_f32 v[244:245], v[172:173], v[172:173], v[244:245]
	v_pk_fma_f32 v[244:245], v[174:175], v[174:175], v[244:245]
	v_cvt_pk_bf16_f32 v148, v168, v169
	v_cvt_pk_bf16_f32 v149, v170, v171
	v_cvt_pk_bf16_f32 v150, v172, v173
	v_cvt_pk_bf16_f32 v151, v174, v175
	global_store_dwordx4 v[164:165], v[148:151], off
	v_lshlrev_b32_e32 v168, 16, v160
	v_and_b32_e32 v169, 0xffff0000, v160
	v_lshlrev_b32_e32 v170, 16, v161
	v_and_b32_e32 v171, 0xffff0000, v161
	v_lshlrev_b32_e32 v172, 16, v162
	v_and_b32_e32 v173, 0xffff0000, v162
	v_lshlrev_b32_e32 v174, 16, v163
	v_and_b32_e32 v175, 0xffff0000, v163
	v_pk_fma_f32 v[168:169], v[118:119], 0.5, v[168:169] op_sel_hi:[1,0,1]
	v_pk_fma_f32 v[170:171], v[120:121], 0.5, v[170:171] op_sel_hi:[1,0,1]
	v_pk_fma_f32 v[172:173], v[114:115], 0.5, v[172:173] op_sel_hi:[1,0,1]
	v_pk_fma_f32 v[174:175], v[116:117], 0.5, v[174:175] op_sel_hi:[1,0,1]
	v_pk_fma_f32 v[244:245], v[168:169], v[168:169], v[244:245]
	v_pk_fma_f32 v[244:245], v[170:171], v[170:171], v[244:245]
	v_pk_fma_f32 v[244:245], v[172:173], v[172:173], v[244:245]
	v_pk_fma_f32 v[244:245], v[174:175], v[174:175], v[244:245]
	v_cvt_pk_bf16_f32 v160, v168, v169
	v_cvt_pk_bf16_f32 v161, v170, v171
	v_cvt_pk_bf16_f32 v162, v172, v173
	v_cvt_pk_bf16_f32 v163, v174, v175
	global_store_dwordx4 v[164:165], v[160:163], off offset:256
	v_add_f32_e32 v246, v244, v245
	v_mov_b32_e32 v247, v246
	s_nop 1
	v_permlane32_swap_b32 v247, v246
	s_nop 1
	v_add_f32_e32 v246, v246, v247
	v_mov_b32_e32 v247, v246
	s_nop 1
	v_permlane16_swap_b32 v247, v246
	s_nop 1
	v_add_f32_e32 v246, v246, v247
	s_mov_b64 exec, s[46:47]
	global_atomic_add_f32 v[166:167], v246, off
	s_mov_b64 exec, -1
	s_mov_b64 vcc, 0x8000
	s_nop 0
	v_lshl_add_u64 v[164:165], v[164:165], 0, vcc
	s_waitcnt vmcnt(16)
	v_lshlrev_b32_e32 v168, 16, v176
	v_and_b32_e32 v169, 0xffff0000, v176
	v_lshlrev_b32_e32 v170, 16, v177
	v_and_b32_e32 v171, 0xffff0000, v177
	v_lshlrev_b32_e32 v172, 16, v178
	v_and_b32_e32 v173, 0xffff0000, v178
	v_lshlrev_b32_e32 v174, 16, v179
	v_and_b32_e32 v175, 0xffff0000, v179
	v_pk_fma_f32 v[168:169], v[110:111], 0.5, v[168:169] op_sel_hi:[1,0,1]
	v_pk_fma_f32 v[170:171], v[112:113], 0.5, v[170:171] op_sel_hi:[1,0,1]
	v_pk_fma_f32 v[172:173], v[106:107], 0.5, v[172:173] op_sel_hi:[1,0,1]
	v_pk_fma_f32 v[174:175], v[108:109], 0.5, v[174:175] op_sel_hi:[1,0,1]
	v_pk_mul_f32 v[244:245], v[168:169], v[168:169]
	v_pk_fma_f32 v[244:245], v[170:171], v[170:171], v[244:245]
	v_pk_fma_f32 v[244:245], v[172:173], v[172:173], v[244:245]
	v_pk_fma_f32 v[244:245], v[174:175], v[174:175], v[244:245]
	v_cvt_pk_bf16_f32 v176, v168, v169
	v_cvt_pk_bf16_f32 v177, v170, v171
	v_cvt_pk_bf16_f32 v178, v172, v173
	v_cvt_pk_bf16_f32 v179, v174, v175
	global_store_dwordx4 v[164:165], v[176:179], off
	v_lshlrev_b32_e32 v168, 16, v180
	v_and_b32_e32 v169, 0xffff0000, v180
	v_lshlrev_b32_e32 v170, 16, v181
	v_and_b32_e32 v171, 0xffff0000, v181
	v_lshlrev_b32_e32 v172, 16, v182
	v_and_b32_e32 v173, 0xffff0000, v182
	v_lshlrev_b32_e32 v174, 16, v183
	v_and_b32_e32 v175, 0xffff0000, v183
	v_pk_fma_f32 v[168:169], v[102:103], 0.5, v[168:169] op_sel_hi:[1,0,1]
	v_pk_fma_f32 v[170:171], v[104:105], 0.5, v[170:171] op_sel_hi:[1,0,1]
	v_pk_fma_f32 v[172:173], v[98:99], 0.5, v[172:173] op_sel_hi:[1,0,1]
	v_pk_fma_f32 v[174:175], v[100:101], 0.5, v[174:175] op_sel_hi:[1,0,1]
	v_pk_fma_f32 v[244:245], v[168:169], v[168:169], v[244:245]
	v_pk_fma_f32 v[244:245], v[170:171], v[170:171], v[244:245]
	v_pk_fma_f32 v[244:245], v[172:173], v[172:173], v[244:245]
	v_pk_fma_f32 v[244:245], v[174:175], v[174:175], v[244:245]
	v_cvt_pk_bf16_f32 v180, v168, v169
	v_cvt_pk_bf16_f32 v181, v170, v171
	v_cvt_pk_bf16_f32 v182, v172, v173
	v_cvt_pk_bf16_f32 v183, v174, v175
	global_store_dwordx4 v[164:165], v[180:183], off offset:256
	v_add_f32_e32 v246, v244, v245
	v_mov_b32_e32 v247, v246
	s_nop 1
	v_permlane32_swap_b32 v247, v246
	s_nop 1
	v_add_f32_e32 v246, v246, v247
	v_mov_b32_e32 v247, v246
	s_nop 1
	v_permlane16_swap_b32 v247, v246
	s_nop 1
	v_add_f32_e32 v246, v246, v247
	s_mov_b64 exec, s[46:47]
	global_atomic_add_f32 v[166:167], v246, off offset:64
	s_mov_b64 exec, -1
	s_mov_b64 vcc, 0x8000
	s_nop 0
	v_lshl_add_u64 v[164:165], v[164:165], 0, vcc
	s_waitcnt vmcnt(17)
	v_lshlrev_b32_e32 v168, 16, v184
	v_and_b32_e32 v169, 0xffff0000, v184
	v_lshlrev_b32_e32 v170, 16, v185
	v_and_b32_e32 v171, 0xffff0000, v185
	v_lshlrev_b32_e32 v172, 16, v186
	v_and_b32_e32 v173, 0xffff0000, v186
	v_lshlrev_b32_e32 v174, 16, v187
	v_and_b32_e32 v175, 0xffff0000, v187
	v_pk_fma_f32 v[168:169], v[94:95], 0.5, v[168:169] op_sel_hi:[1,0,1]
	v_pk_fma_f32 v[170:171], v[96:97], 0.5, v[170:171] op_sel_hi:[1,0,1]
	v_pk_fma_f32 v[172:173], v[90:91], 0.5, v[172:173] op_sel_hi:[1,0,1]
	v_pk_fma_f32 v[174:175], v[92:93], 0.5, v[174:175] op_sel_hi:[1,0,1]
	v_pk_mul_f32 v[244:245], v[168:169], v[168:169]
	v_pk_fma_f32 v[244:245], v[170:171], v[170:171], v[244:245]
	v_pk_fma_f32 v[244:245], v[172:173], v[172:173], v[244:245]
	v_pk_fma_f32 v[244:245], v[174:175], v[174:175], v[244:245]
	v_cvt_pk_bf16_f32 v184, v168, v169
	v_cvt_pk_bf16_f32 v185, v170, v171
	v_cvt_pk_bf16_f32 v186, v172, v173
	v_cvt_pk_bf16_f32 v187, v174, v175
	global_store_dwordx4 v[164:165], v[184:187], off
	v_lshlrev_b32_e32 v168, 16, v188
	v_and_b32_e32 v169, 0xffff0000, v188
	v_lshlrev_b32_e32 v170, 16, v189
	v_and_b32_e32 v171, 0xffff0000, v189
	v_lshlrev_b32_e32 v172, 16, v190
	v_and_b32_e32 v173, 0xffff0000, v190
	v_lshlrev_b32_e32 v174, 16, v191
	v_and_b32_e32 v175, 0xffff0000, v191
	v_pk_fma_f32 v[168:169], v[86:87], 0.5, v[168:169] op_sel_hi:[1,0,1]
	v_pk_fma_f32 v[170:171], v[88:89], 0.5, v[170:171] op_sel_hi:[1,0,1]
	v_pk_fma_f32 v[172:173], v[82:83], 0.5, v[172:173] op_sel_hi:[1,0,1]
	v_pk_fma_f32 v[174:175], v[84:85], 0.5, v[174:175] op_sel_hi:[1,0,1]
	v_pk_fma_f32 v[244:245], v[168:169], v[168:169], v[244:245]
	v_pk_fma_f32 v[244:245], v[170:171], v[170:171], v[244:245]
	v_pk_fma_f32 v[244:245], v[172:173], v[172:173], v[244:245]
	v_pk_fma_f32 v[244:245], v[174:175], v[174:175], v[244:245]
	v_cvt_pk_bf16_f32 v188, v168, v169
	v_cvt_pk_bf16_f32 v189, v170, v171
	v_cvt_pk_bf16_f32 v190, v172, v173
	v_cvt_pk_bf16_f32 v191, v174, v175
	global_store_dwordx4 v[164:165], v[188:191], off offset:256
	v_add_f32_e32 v246, v244, v245
	v_mov_b32_e32 v247, v246
	s_nop 1
	v_permlane32_swap_b32 v247, v246
	s_nop 1
	v_add_f32_e32 v246, v246, v247
	v_mov_b32_e32 v247, v246
	s_nop 1
	v_permlane16_swap_b32 v247, v246
	s_nop 1
	v_add_f32_e32 v246, v246, v247
	s_mov_b64 exec, s[46:47]
	global_atomic_add_f32 v[166:167], v246, off offset:128
	s_mov_b64 exec, -1
	s_mov_b64 vcc, 0x8000
	s_nop 0
	v_lshl_add_u64 v[164:165], v[164:165], 0, vcc
	s_waitcnt vmcnt(18)
	v_lshlrev_b32_e32 v168, 16, v204
	v_and_b32_e32 v169, 0xffff0000, v204
	v_lshlrev_b32_e32 v170, 16, v205
	v_and_b32_e32 v171, 0xffff0000, v205
	v_lshlrev_b32_e32 v172, 16, v206
	v_and_b32_e32 v173, 0xffff0000, v206
	v_lshlrev_b32_e32 v174, 16, v207
	v_and_b32_e32 v175, 0xffff0000, v207
	v_pk_fma_f32 v[168:169], v[76:77], 0.5, v[168:169] op_sel_hi:[1,0,1]
	v_pk_fma_f32 v[170:171], v[78:79], 0.5, v[170:171] op_sel_hi:[1,0,1]
	v_pk_fma_f32 v[172:173], v[72:73], 0.5, v[172:173] op_sel_hi:[1,0,1]
	v_pk_fma_f32 v[174:175], v[74:75], 0.5, v[174:175] op_sel_hi:[1,0,1]
	v_pk_mul_f32 v[244:245], v[168:169], v[168:169]
	v_pk_fma_f32 v[244:245], v[170:171], v[170:171], v[244:245]
	v_pk_fma_f32 v[244:245], v[172:173], v[172:173], v[244:245]
	v_pk_fma_f32 v[244:245], v[174:175], v[174:175], v[244:245]
	v_cvt_pk_bf16_f32 v204, v168, v169
	v_cvt_pk_bf16_f32 v205, v170, v171
	v_cvt_pk_bf16_f32 v206, v172, v173
	v_cvt_pk_bf16_f32 v207, v174, v175
	global_store_dwordx4 v[164:165], v[204:207], off
	v_lshlrev_b32_e32 v168, 16, v208
	v_and_b32_e32 v169, 0xffff0000, v208
	v_lshlrev_b32_e32 v170, 16, v209
	v_and_b32_e32 v171, 0xffff0000, v209
	v_lshlrev_b32_e32 v172, 16, v210
	v_and_b32_e32 v173, 0xffff0000, v210
	v_lshlrev_b32_e32 v174, 16, v211
	v_and_b32_e32 v175, 0xffff0000, v211
	v_pk_fma_f32 v[168:169], v[68:69], 0.5, v[168:169] op_sel_hi:[1,0,1]
	v_pk_fma_f32 v[170:171], v[70:71], 0.5, v[170:171] op_sel_hi:[1,0,1]
	v_pk_fma_f32 v[172:173], v[64:65], 0.5, v[172:173] op_sel_hi:[1,0,1]
	v_pk_fma_f32 v[174:175], v[66:67], 0.5, v[174:175] op_sel_hi:[1,0,1]
	v_pk_fma_f32 v[244:245], v[168:169], v[168:169], v[244:245]
	v_pk_fma_f32 v[244:245], v[170:171], v[170:171], v[244:245]
	v_pk_fma_f32 v[244:245], v[172:173], v[172:173], v[244:245]
	v_pk_fma_f32 v[244:245], v[174:175], v[174:175], v[244:245]
	v_cvt_pk_bf16_f32 v208, v168, v169
	v_cvt_pk_bf16_f32 v209, v170, v171
	v_cvt_pk_bf16_f32 v210, v172, v173
	v_cvt_pk_bf16_f32 v211, v174, v175
	global_store_dwordx4 v[164:165], v[208:211], off offset:256
	v_add_f32_e32 v246, v244, v245
	v_mov_b32_e32 v247, v246
	s_nop 1
	v_permlane32_swap_b32 v247, v246
	s_nop 1
	v_add_f32_e32 v246, v246, v247
	v_mov_b32_e32 v247, v246
	s_nop 1
	v_permlane16_swap_b32 v247, v246
	s_nop 1
	v_add_f32_e32 v246, v246, v247
	s_mov_b64 exec, s[46:47]
	global_atomic_add_f32 v[166:167], v246, off offset:192
	s_mov_b64 exec, -1
	s_mov_b64 vcc, 0x28000
	s_nop 0
	v_lshl_add_u64 v[164:165], v[164:165], 0, vcc
	s_waitcnt vmcnt(19)
	v_lshlrev_b32_e32 v168, 16, v212
	v_and_b32_e32 v169, 0xffff0000, v212
	v_lshlrev_b32_e32 v170, 16, v213
	v_and_b32_e32 v171, 0xffff0000, v213
	v_lshlrev_b32_e32 v172, 16, v214
	v_and_b32_e32 v173, 0xffff0000, v214
	v_lshlrev_b32_e32 v174, 16, v215
	v_and_b32_e32 v175, 0xffff0000, v215
	v_pk_fma_f32 v[168:169], v[60:61], 0.5, v[168:169] op_sel_hi:[1,0,1]
	v_pk_fma_f32 v[170:171], v[62:63], 0.5, v[170:171] op_sel_hi:[1,0,1]
	v_pk_fma_f32 v[172:173], v[56:57], 0.5, v[172:173] op_sel_hi:[1,0,1]
	v_pk_fma_f32 v[174:175], v[58:59], 0.5, v[174:175] op_sel_hi:[1,0,1]
	v_pk_mul_f32 v[244:245], v[168:169], v[168:169]
	v_pk_fma_f32 v[244:245], v[170:171], v[170:171], v[244:245]
	v_pk_fma_f32 v[244:245], v[172:173], v[172:173], v[244:245]
	v_pk_fma_f32 v[244:245], v[174:175], v[174:175], v[244:245]
	v_cvt_pk_bf16_f32 v212, v168, v169
	v_cvt_pk_bf16_f32 v213, v170, v171
	v_cvt_pk_bf16_f32 v214, v172, v173
	v_cvt_pk_bf16_f32 v215, v174, v175
	global_store_dwordx4 v[164:165], v[212:215], off
	v_lshlrev_b32_e32 v168, 16, v216
	v_and_b32_e32 v169, 0xffff0000, v216
	v_lshlrev_b32_e32 v170, 16, v217
	v_and_b32_e32 v171, 0xffff0000, v217
	v_lshlrev_b32_e32 v172, 16, v218
	v_and_b32_e32 v173, 0xffff0000, v218
	v_lshlrev_b32_e32 v174, 16, v219
	v_and_b32_e32 v175, 0xffff0000, v219
	v_pk_fma_f32 v[168:169], v[52:53], 0.5, v[168:169] op_sel_hi:[1,0,1]
	v_pk_fma_f32 v[170:171], v[54:55], 0.5, v[170:171] op_sel_hi:[1,0,1]
	v_pk_fma_f32 v[172:173], v[48:49], 0.5, v[172:173] op_sel_hi:[1,0,1]
	v_pk_fma_f32 v[174:175], v[50:51], 0.5, v[174:175] op_sel_hi:[1,0,1]
	v_pk_fma_f32 v[244:245], v[168:169], v[168:169], v[244:245]
	v_pk_fma_f32 v[244:245], v[170:171], v[170:171], v[244:245]
	v_pk_fma_f32 v[244:245], v[172:173], v[172:173], v[244:245]
	v_pk_fma_f32 v[244:245], v[174:175], v[174:175], v[244:245]
	v_cvt_pk_bf16_f32 v216, v168, v169
	v_cvt_pk_bf16_f32 v217, v170, v171
	v_cvt_pk_bf16_f32 v218, v172, v173
	v_cvt_pk_bf16_f32 v219, v174, v175
	global_store_dwordx4 v[164:165], v[216:219], off offset:256
	v_add_f32_e32 v246, v244, v245
	v_mov_b32_e32 v247, v246
	s_nop 1
	v_permlane32_swap_b32 v247, v246
	s_nop 1
	v_add_f32_e32 v246, v246, v247
	v_mov_b32_e32 v247, v246
	s_nop 1
	v_permlane16_swap_b32 v247, v246
	s_nop 1
	v_add_f32_e32 v246, v246, v247
	s_mov_b64 exec, s[46:47]
	global_atomic_add_f32 v[166:167], v246, off offset:512
	s_mov_b64 exec, -1
	s_mov_b64 vcc, 0x8000
	s_nop 0
	v_lshl_add_u64 v[164:165], v[164:165], 0, vcc
	s_waitcnt vmcnt(20)
	v_lshlrev_b32_e32 v168, 16, v220
	v_and_b32_e32 v169, 0xffff0000, v220
	v_lshlrev_b32_e32 v170, 16, v221
	v_and_b32_e32 v171, 0xffff0000, v221
	v_lshlrev_b32_e32 v172, 16, v222
	v_and_b32_e32 v173, 0xffff0000, v222
	v_lshlrev_b32_e32 v174, 16, v223
	v_and_b32_e32 v175, 0xffff0000, v223
	v_pk_fma_f32 v[168:169], v[44:45], 0.5, v[168:169] op_sel_hi:[1,0,1]
	v_pk_fma_f32 v[170:171], v[46:47], 0.5, v[170:171] op_sel_hi:[1,0,1]
	v_pk_fma_f32 v[172:173], v[40:41], 0.5, v[172:173] op_sel_hi:[1,0,1]
	v_pk_fma_f32 v[174:175], v[42:43], 0.5, v[174:175] op_sel_hi:[1,0,1]
	v_pk_mul_f32 v[244:245], v[168:169], v[168:169]
	v_pk_fma_f32 v[244:245], v[170:171], v[170:171], v[244:245]
	v_pk_fma_f32 v[244:245], v[172:173], v[172:173], v[244:245]
	v_pk_fma_f32 v[244:245], v[174:175], v[174:175], v[244:245]
	v_cvt_pk_bf16_f32 v220, v168, v169
	v_cvt_pk_bf16_f32 v221, v170, v171
	v_cvt_pk_bf16_f32 v222, v172, v173
	v_cvt_pk_bf16_f32 v223, v174, v175
	global_store_dwordx4 v[164:165], v[220:223], off
	v_lshlrev_b32_e32 v168, 16, v224
	v_and_b32_e32 v169, 0xffff0000, v224
	v_lshlrev_b32_e32 v170, 16, v225
	v_and_b32_e32 v171, 0xffff0000, v225
	v_lshlrev_b32_e32 v172, 16, v226
	v_and_b32_e32 v173, 0xffff0000, v226
	v_lshlrev_b32_e32 v174, 16, v227
	v_and_b32_e32 v175, 0xffff0000, v227
	v_pk_fma_f32 v[168:169], v[36:37], 0.5, v[168:169] op_sel_hi:[1,0,1]
	v_pk_fma_f32 v[170:171], v[38:39], 0.5, v[170:171] op_sel_hi:[1,0,1]
	v_pk_fma_f32 v[172:173], v[32:33], 0.5, v[172:173] op_sel_hi:[1,0,1]
	v_pk_fma_f32 v[174:175], v[34:35], 0.5, v[174:175] op_sel_hi:[1,0,1]
	v_pk_fma_f32 v[244:245], v[168:169], v[168:169], v[244:245]
	v_pk_fma_f32 v[244:245], v[170:171], v[170:171], v[244:245]
	v_pk_fma_f32 v[244:245], v[172:173], v[172:173], v[244:245]
	v_pk_fma_f32 v[244:245], v[174:175], v[174:175], v[244:245]
	v_cvt_pk_bf16_f32 v224, v168, v169
	v_cvt_pk_bf16_f32 v225, v170, v171
	v_cvt_pk_bf16_f32 v226, v172, v173
	v_cvt_pk_bf16_f32 v227, v174, v175
	global_store_dwordx4 v[164:165], v[224:227], off offset:256
	v_add_f32_e32 v246, v244, v245
	v_mov_b32_e32 v247, v246
	s_nop 1
	v_permlane32_swap_b32 v247, v246
	s_nop 1
	v_add_f32_e32 v246, v246, v247
	v_mov_b32_e32 v247, v246
	s_nop 1
	v_permlane16_swap_b32 v247, v246
	s_nop 1
	v_add_f32_e32 v246, v246, v247
	s_mov_b64 exec, s[46:47]
	global_atomic_add_f32 v[166:167], v246, off offset:576
	s_mov_b64 exec, -1
	s_mov_b64 vcc, 0x8000
	s_nop 0
	v_lshl_add_u64 v[164:165], v[164:165], 0, vcc
	s_waitcnt vmcnt(21)
	v_lshlrev_b32_e32 v168, 16, v228
	v_and_b32_e32 v169, 0xffff0000, v228
	v_lshlrev_b32_e32 v170, 16, v229
	v_and_b32_e32 v171, 0xffff0000, v229
	v_lshlrev_b32_e32 v172, 16, v230
	v_and_b32_e32 v173, 0xffff0000, v230
	v_lshlrev_b32_e32 v174, 16, v231
	v_and_b32_e32 v175, 0xffff0000, v231
	v_pk_fma_f32 v[168:169], v[28:29], 0.5, v[168:169] op_sel_hi:[1,0,1]
	v_pk_fma_f32 v[170:171], v[30:31], 0.5, v[170:171] op_sel_hi:[1,0,1]
	v_pk_fma_f32 v[172:173], v[24:25], 0.5, v[172:173] op_sel_hi:[1,0,1]
	v_pk_fma_f32 v[174:175], v[26:27], 0.5, v[174:175] op_sel_hi:[1,0,1]
	v_pk_mul_f32 v[244:245], v[168:169], v[168:169]
	v_pk_fma_f32 v[244:245], v[170:171], v[170:171], v[244:245]
	v_pk_fma_f32 v[244:245], v[172:173], v[172:173], v[244:245]
	v_pk_fma_f32 v[244:245], v[174:175], v[174:175], v[244:245]
	v_cvt_pk_bf16_f32 v228, v168, v169
	v_cvt_pk_bf16_f32 v229, v170, v171
	v_cvt_pk_bf16_f32 v230, v172, v173
	v_cvt_pk_bf16_f32 v231, v174, v175
	global_store_dwordx4 v[164:165], v[228:231], off
	v_lshlrev_b32_e32 v168, 16, v232
	v_and_b32_e32 v169, 0xffff0000, v232
	v_lshlrev_b32_e32 v170, 16, v233
	v_and_b32_e32 v171, 0xffff0000, v233
	v_lshlrev_b32_e32 v172, 16, v234
	v_and_b32_e32 v173, 0xffff0000, v234
	v_lshlrev_b32_e32 v174, 16, v235
	v_and_b32_e32 v175, 0xffff0000, v235
	v_pk_fma_f32 v[168:169], v[20:21], 0.5, v[168:169] op_sel_hi:[1,0,1]
	v_pk_fma_f32 v[170:171], v[22:23], 0.5, v[170:171] op_sel_hi:[1,0,1]
	v_pk_fma_f32 v[172:173], v[16:17], 0.5, v[172:173] op_sel_hi:[1,0,1]
	v_pk_fma_f32 v[174:175], v[18:19], 0.5, v[174:175] op_sel_hi:[1,0,1]
	v_pk_fma_f32 v[244:245], v[168:169], v[168:169], v[244:245]
	v_pk_fma_f32 v[244:245], v[170:171], v[170:171], v[244:245]
	v_pk_fma_f32 v[244:245], v[172:173], v[172:173], v[244:245]
	v_pk_fma_f32 v[244:245], v[174:175], v[174:175], v[244:245]
	v_cvt_pk_bf16_f32 v232, v168, v169
	v_cvt_pk_bf16_f32 v233, v170, v171
	v_cvt_pk_bf16_f32 v234, v172, v173
	v_cvt_pk_bf16_f32 v235, v174, v175
	global_store_dwordx4 v[164:165], v[232:235], off offset:256
	v_add_f32_e32 v246, v244, v245
	v_mov_b32_e32 v247, v246
	s_nop 1
	v_permlane32_swap_b32 v247, v246
	s_nop 1
	v_add_f32_e32 v246, v246, v247
	v_mov_b32_e32 v247, v246
	s_nop 1
	v_permlane16_swap_b32 v247, v246
	s_nop 1
	v_add_f32_e32 v246, v246, v247
	s_mov_b64 exec, s[46:47]
	global_atomic_add_f32 v[166:167], v246, off offset:640
	s_mov_b64 exec, -1
	s_mov_b64 vcc, 0x8000
	s_nop 0
	v_lshl_add_u64 v[164:165], v[164:165], 0, vcc
	s_waitcnt vmcnt(22)
	v_lshlrev_b32_e32 v168, 16, v236
	v_and_b32_e32 v169, 0xffff0000, v236
	v_lshlrev_b32_e32 v170, 16, v237
	v_and_b32_e32 v171, 0xffff0000, v237
	v_lshlrev_b32_e32 v172, 16, v238
	v_and_b32_e32 v173, 0xffff0000, v238
	v_lshlrev_b32_e32 v174, 16, v239
	v_and_b32_e32 v175, 0xffff0000, v239
	v_pk_fma_f32 v[168:169], v[12:13], 0.5, v[168:169] op_sel_hi:[1,0,1]
	v_pk_fma_f32 v[170:171], v[14:15], 0.5, v[170:171] op_sel_hi:[1,0,1]
	v_pk_fma_f32 v[172:173], v[8:9], 0.5, v[172:173] op_sel_hi:[1,0,1]
	v_pk_fma_f32 v[174:175], v[10:11], 0.5, v[174:175] op_sel_hi:[1,0,1]
	v_pk_mul_f32 v[244:245], v[168:169], v[168:169]
	v_pk_fma_f32 v[244:245], v[170:171], v[170:171], v[244:245]
	v_pk_fma_f32 v[244:245], v[172:173], v[172:173], v[244:245]
	v_pk_fma_f32 v[244:245], v[174:175], v[174:175], v[244:245]
	v_cvt_pk_bf16_f32 v236, v168, v169
	v_cvt_pk_bf16_f32 v237, v170, v171
	v_cvt_pk_bf16_f32 v238, v172, v173
	v_cvt_pk_bf16_f32 v239, v174, v175
	global_store_dwordx4 v[164:165], v[236:239], off
	v_lshlrev_b32_e32 v168, 16, v240
	v_and_b32_e32 v169, 0xffff0000, v240
	v_lshlrev_b32_e32 v170, 16, v241
	v_and_b32_e32 v171, 0xffff0000, v241
	v_lshlrev_b32_e32 v172, 16, v242
	v_and_b32_e32 v173, 0xffff0000, v242
	v_lshlrev_b32_e32 v174, 16, v243
	v_and_b32_e32 v175, 0xffff0000, v243
	v_pk_fma_f32 v[168:169], v[4:5], 0.5, v[168:169] op_sel_hi:[1,0,1]
	v_pk_fma_f32 v[170:171], v[6:7], 0.5, v[170:171] op_sel_hi:[1,0,1]
	v_pk_fma_f32 v[172:173], v[0:1], 0.5, v[172:173] op_sel_hi:[1,0,1]
	v_pk_fma_f32 v[174:175], v[2:3], 0.5, v[174:175] op_sel_hi:[1,0,1]
	v_pk_fma_f32 v[244:245], v[168:169], v[168:169], v[244:245]
	v_pk_fma_f32 v[244:245], v[170:171], v[170:171], v[244:245]
	v_pk_fma_f32 v[244:245], v[172:173], v[172:173], v[244:245]
	v_pk_fma_f32 v[244:245], v[174:175], v[174:175], v[244:245]
	v_cvt_pk_bf16_f32 v240, v168, v169
	v_cvt_pk_bf16_f32 v241, v170, v171
	v_cvt_pk_bf16_f32 v242, v172, v173
	v_cvt_pk_bf16_f32 v243, v174, v175
	global_store_dwordx4 v[164:165], v[240:243], off offset:256
	v_add_f32_e32 v246, v244, v245
	v_mov_b32_e32 v247, v246
	s_nop 1
	v_permlane32_swap_b32 v247, v246
	s_nop 1
	v_add_f32_e32 v246, v246, v247
	v_mov_b32_e32 v247, v246
	s_nop 1
	v_permlane16_swap_b32 v247, v246
	s_nop 1
	v_add_f32_e32 v246, v246, v247
	s_mov_b64 exec, s[46:47]
	global_atomic_add_f32 v[166:167], v246, off offset:704
	s_mov_b64 exec, -1
	s_mov_b64 s[40:41], exec
	s_branch .LBB0_212

.LBB0_643:
	v_ashrrev_i32_e32 v142, 2, v192
	v_and_b32_e32 v142, 0xffffffc0, v142
	s_lshl_b32 vcc_lo, s53, 8
	v_and_or_b32 v143, v192, 15, vcc_lo
	v_add_u32_e32 v142, v143, v142
	v_ashrrev_i32_e32 v143, 31, v142
	v_bfe_u32 v147, v192, 4, 2
	v_lshrrev_b32_e32 v80, 1, v192
	v_and_b32_e32 v80, 0x60, v80
	s_lshl_b32 vcc_lo, s52, 8
	v_add_u32_e32 v80, vcc_lo, v80
	v_lshl_add_u32 v80, v147, 3, v80
	v_lshlrev_b32_e32 v80, 1, v80
	v_lshlrev_b64 v[164:165], 11, v[142:143]
	v_lshl_add_u64 v[164:165], s[38:39], 0, v[164:165]
	v_lshl_add_u64 v[164:165], v[164:165], 0, v[80:81]
	v_mov_b32_e32 v248, v164
	v_mov_b32_e32 v249, v165
	global_load_dwordx4 v[148:151], v[248:249], off
	global_load_dwordx4 v[160:163], v[248:249], off offset:256
	s_mov_b64 vcc, 0x8000
	s_nop 0
	v_lshl_add_u64 v[248:249], v[248:249], 0, vcc
	global_load_dwordx4 v[176:179], v[248:249], off
	global_load_dwordx4 v[180:183], v[248:249], off offset:256
	s_mov_b64 vcc, 0x8000
	s_nop 0
	v_lshl_add_u64 v[248:249], v[248:249], 0, vcc
	global_load_dwordx4 v[184:187], v[248:249], off
	global_load_dwordx4 v[188:191], v[248:249], off offset:256
	s_mov_b64 vcc, 0x8000
	s_nop 0
	v_lshl_add_u64 v[248:249], v[248:249], 0, vcc
	global_load_dwordx4 v[204:207], v[248:249], off
	global_load_dwordx4 v[208:211], v[248:249], off offset:256
	s_mov_b64 vcc, 0x28000
	s_nop 0
	v_lshl_add_u64 v[248:249], v[248:249], 0, vcc
	global_load_dwordx4 v[212:215], v[248:249], off
	global_load_dwordx4 v[216:219], v[248:249], off offset:256
	s_mov_b64 vcc, 0x8000
	s_nop 0
	v_lshl_add_u64 v[248:249], v[248:249], 0, vcc
	global_load_dwordx4 v[220:223], v[248:249], off
	global_load_dwordx4 v[224:227], v[248:249], off offset:256
	s_mov_b64 vcc, 0x8000
	s_nop 0
	v_lshl_add_u64 v[248:249], v[248:249], 0, vcc
	global_load_dwordx4 v[228:231], v[248:249], off
	global_load_dwordx4 v[232:235], v[248:249], off offset:256
	s_mov_b64 vcc, 0x8000
	s_nop 0
	v_lshl_add_u64 v[248:249], v[248:249], 0, vcc
	global_load_dwordx4 v[236:239], v[248:249], off
	global_load_dwordx4 v[240:243], v[248:249], off offset:256
	v_cmp_eq_u32_e64 s[46:47], 0, v147
	s_nop 0
	v_lshl_add_u64 v[166:167], v[142:143], 2, s[26:27]
	s_waitcnt vmcnt(15)
	v_lshlrev_b32_e32 v168, 16, v148
	v_and_b32_e32 v169, 0xffff0000, v148
	v_lshlrev_b32_e32 v170, 16, v149
	v_and_b32_e32 v171, 0xffff0000, v149
	v_lshlrev_b32_e32 v172, 16, v150
	v_and_b32_e32 v173, 0xffff0000, v150
	v_lshlrev_b32_e32 v174, 16, v151
	v_and_b32_e32 v175, 0xffff0000, v151
	v_pk_fma_f32 v[168:169], v[126:127], 0.5, v[168:169] op_sel_hi:[1,0,1]
	v_pk_fma_f32 v[170:171], v[128:129], 0.5, v[170:171] op_sel_hi:[1,0,1]
	v_pk_fma_f32 v[172:173], v[122:123], 0.5, v[172:173] op_sel_hi:[1,0,1]
	v_pk_fma_f32 v[174:175], v[124:125], 0.5, v[174:175] op_sel_hi:[1,0,1]
	v_pk_mul_f32 v[244:245], v[168:169], v[168:169]
	v_pk_fma_f32 v[244:245], v[170:171], v[170:171], v[244:245]
	v_pk_fma_f32 v[244:245], v[172:173], v[172:173], v[244:245]
	v_pk_fma_f32 v[244:245], v[174:175], v[174:175], v[244:245]
	v_cvt_pk_bf16_f32 v148, v168, v169
	v_cvt_pk_bf16_f32 v149, v170, v171
	v_cvt_pk_bf16_f32 v150, v172, v173
	v_cvt_pk_bf16_f32 v151, v174, v175
	global_store_dwordx4 v[164:165], v[148:151], off
	v_lshlrev_b32_e32 v168, 16, v160
	v_and_b32_e32 v169, 0xffff0000, v160
	v_lshlrev_b32_e32 v170, 16, v161
	v_and_b32_e32 v171, 0xffff0000, v161
	v_lshlrev_b32_e32 v172, 16, v162
	v_and_b32_e32 v173, 0xffff0000, v162
	v_lshlrev_b32_e32 v174, 16, v163
	v_and_b32_e32 v175, 0xffff0000, v163
	v_pk_fma_f32 v[168:169], v[118:119], 0.5, v[168:169] op_sel_hi:[1,0,1]
	v_pk_fma_f32 v[170:171], v[120:121], 0.5, v[170:171] op_sel_hi:[1,0,1]
	v_pk_fma_f32 v[172:173], v[114:115], 0.5, v[172:173] op_sel_hi:[1,0,1]
	v_pk_fma_f32 v[174:175], v[116:117], 0.5, v[174:175] op_sel_hi:[1,0,1]
	v_pk_fma_f32 v[244:245], v[168:169], v[168:169], v[244:245]
	v_pk_fma_f32 v[244:245], v[170:171], v[170:171], v[244:245]
	v_pk_fma_f32 v[244:245], v[172:173], v[172:173], v[244:245]
	v_pk_fma_f32 v[244:245], v[174:175], v[174:175], v[244:245]
	v_cvt_pk_bf16_f32 v160, v168, v169
	v_cvt_pk_bf16_f32 v161, v170, v171
	v_cvt_pk_bf16_f32 v162, v172, v173
	v_cvt_pk_bf16_f32 v163, v174, v175
	global_store_dwordx4 v[164:165], v[160:163], off offset:256
	v_add_f32_e32 v246, v244, v245
	v_mov_b32_e32 v247, v246
	s_nop 1
	v_permlane32_swap_b32 v247, v246
	s_nop 1
	v_add_f32_e32 v246, v246, v247
	v_mov_b32_e32 v247, v246
	s_nop 1
	v_permlane16_swap_b32 v247, v246
	s_nop 1
	v_add_f32_e32 v246, v246, v247
	s_mov_b64 exec, s[46:47]
	global_atomic_add_f32 v[166:167], v246, off
	s_mov_b64 exec, -1
	s_mov_b64 vcc, 0x8000
	s_nop 0
	v_lshl_add_u64 v[164:165], v[164:165], 0, vcc
	s_waitcnt vmcnt(16)
	v_lshlrev_b32_e32 v168, 16, v176
	v_and_b32_e32 v169, 0xffff0000, v176
	v_lshlrev_b32_e32 v170, 16, v177
	v_and_b32_e32 v171, 0xffff0000, v177
	v_lshlrev_b32_e32 v172, 16, v178
	v_and_b32_e32 v173, 0xffff0000, v178
	v_lshlrev_b32_e32 v174, 16, v179
	v_and_b32_e32 v175, 0xffff0000, v179
	v_pk_fma_f32 v[168:169], v[110:111], 0.5, v[168:169] op_sel_hi:[1,0,1]
	v_pk_fma_f32 v[170:171], v[112:113], 0.5, v[170:171] op_sel_hi:[1,0,1]
	v_pk_fma_f32 v[172:173], v[106:107], 0.5, v[172:173] op_sel_hi:[1,0,1]
	v_pk_fma_f32 v[174:175], v[108:109], 0.5, v[174:175] op_sel_hi:[1,0,1]
	v_pk_mul_f32 v[244:245], v[168:169], v[168:169]
	v_pk_fma_f32 v[244:245], v[170:171], v[170:171], v[244:245]
	v_pk_fma_f32 v[244:245], v[172:173], v[172:173], v[244:245]
	v_pk_fma_f32 v[244:245], v[174:175], v[174:175], v[244:245]
	v_cvt_pk_bf16_f32 v176, v168, v169
	v_cvt_pk_bf16_f32 v177, v170, v171
	v_cvt_pk_bf16_f32 v178, v172, v173
	v_cvt_pk_bf16_f32 v179, v174, v175
	global_store_dwordx4 v[164:165], v[176:179], off
	v_lshlrev_b32_e32 v168, 16, v180
	v_and_b32_e32 v169, 0xffff0000, v180
	v_lshlrev_b32_e32 v170, 16, v181
	v_and_b32_e32 v171, 0xffff0000, v181
	v_lshlrev_b32_e32 v172, 16, v182
	v_and_b32_e32 v173, 0xffff0000, v182
	v_lshlrev_b32_e32 v174, 16, v183
	v_and_b32_e32 v175, 0xffff0000, v183
	v_pk_fma_f32 v[168:169], v[102:103], 0.5, v[168:169] op_sel_hi:[1,0,1]
	v_pk_fma_f32 v[170:171], v[104:105], 0.5, v[170:171] op_sel_hi:[1,0,1]
	v_pk_fma_f32 v[172:173], v[98:99], 0.5, v[172:173] op_sel_hi:[1,0,1]
	v_pk_fma_f32 v[174:175], v[100:101], 0.5, v[174:175] op_sel_hi:[1,0,1]
	v_pk_fma_f32 v[244:245], v[168:169], v[168:169], v[244:245]
	v_pk_fma_f32 v[244:245], v[170:171], v[170:171], v[244:245]
	v_pk_fma_f32 v[244:245], v[172:173], v[172:173], v[244:245]
	v_pk_fma_f32 v[244:245], v[174:175], v[174:175], v[244:245]
	v_cvt_pk_bf16_f32 v180, v168, v169
	v_cvt_pk_bf16_f32 v181, v170, v171
	v_cvt_pk_bf16_f32 v182, v172, v173
	v_cvt_pk_bf16_f32 v183, v174, v175
	global_store_dwordx4 v[164:165], v[180:183], off offset:256
	v_add_f32_e32 v246, v244, v245
	v_mov_b32_e32 v247, v246
	s_nop 1
	v_permlane32_swap_b32 v247, v246
	s_nop 1
	v_add_f32_e32 v246, v246, v247
	v_mov_b32_e32 v247, v246
	s_nop 1
	v_permlane16_swap_b32 v247, v246
	s_nop 1
	v_add_f32_e32 v246, v246, v247
	s_mov_b64 exec, s[46:47]
	global_atomic_add_f32 v[166:167], v246, off offset:64
	s_mov_b64 exec, -1
	s_mov_b64 vcc, 0x8000
	s_nop 0
	v_lshl_add_u64 v[164:165], v[164:165], 0, vcc
	s_waitcnt vmcnt(17)
	v_lshlrev_b32_e32 v168, 16, v184
	v_and_b32_e32 v169, 0xffff0000, v184
	v_lshlrev_b32_e32 v170, 16, v185
	v_and_b32_e32 v171, 0xffff0000, v185
	v_lshlrev_b32_e32 v172, 16, v186
	v_and_b32_e32 v173, 0xffff0000, v186
	v_lshlrev_b32_e32 v174, 16, v187
	v_and_b32_e32 v175, 0xffff0000, v187
	v_pk_fma_f32 v[168:169], v[94:95], 0.5, v[168:169] op_sel_hi:[1,0,1]
	v_pk_fma_f32 v[170:171], v[96:97], 0.5, v[170:171] op_sel_hi:[1,0,1]
	v_pk_fma_f32 v[172:173], v[90:91], 0.5, v[172:173] op_sel_hi:[1,0,1]
	v_pk_fma_f32 v[174:175], v[92:93], 0.5, v[174:175] op_sel_hi:[1,0,1]
	v_pk_mul_f32 v[244:245], v[168:169], v[168:169]
	v_pk_fma_f32 v[244:245], v[170:171], v[170:171], v[244:245]
	v_pk_fma_f32 v[244:245], v[172:173], v[172:173], v[244:245]
	v_pk_fma_f32 v[244:245], v[174:175], v[174:175], v[244:245]
	v_cvt_pk_bf16_f32 v184, v168, v169
	v_cvt_pk_bf16_f32 v185, v170, v171
	v_cvt_pk_bf16_f32 v186, v172, v173
	v_cvt_pk_bf16_f32 v187, v174, v175
	global_store_dwordx4 v[164:165], v[184:187], off
	v_lshlrev_b32_e32 v168, 16, v188
	v_and_b32_e32 v169, 0xffff0000, v188
	v_lshlrev_b32_e32 v170, 16, v189
	v_and_b32_e32 v171, 0xffff0000, v189
	v_lshlrev_b32_e32 v172, 16, v190
	v_and_b32_e32 v173, 0xffff0000, v190
	v_lshlrev_b32_e32 v174, 16, v191
	v_and_b32_e32 v175, 0xffff0000, v191
	v_pk_fma_f32 v[168:169], v[86:87], 0.5, v[168:169] op_sel_hi:[1,0,1]
	v_pk_fma_f32 v[170:171], v[88:89], 0.5, v[170:171] op_sel_hi:[1,0,1]
	v_pk_fma_f32 v[172:173], v[82:83], 0.5, v[172:173] op_sel_hi:[1,0,1]
	v_pk_fma_f32 v[174:175], v[84:85], 0.5, v[174:175] op_sel_hi:[1,0,1]
	v_pk_fma_f32 v[244:245], v[168:169], v[168:169], v[244:245]
	v_pk_fma_f32 v[244:245], v[170:171], v[170:171], v[244:245]
	v_pk_fma_f32 v[244:245], v[172:173], v[172:173], v[244:245]
	v_pk_fma_f32 v[244:245], v[174:175], v[174:175], v[244:245]
	v_cvt_pk_bf16_f32 v188, v168, v169
	v_cvt_pk_bf16_f32 v189, v170, v171
	v_cvt_pk_bf16_f32 v190, v172, v173
	v_cvt_pk_bf16_f32 v191, v174, v175
	global_store_dwordx4 v[164:165], v[188:191], off offset:256
	v_add_f32_e32 v246, v244, v245
	v_mov_b32_e32 v247, v246
	s_nop 1
	v_permlane32_swap_b32 v247, v246
	s_nop 1
	v_add_f32_e32 v246, v246, v247
	v_mov_b32_e32 v247, v246
	s_nop 1
	v_permlane16_swap_b32 v247, v246
	s_nop 1
	v_add_f32_e32 v246, v246, v247
	s_mov_b64 exec, s[46:47]
	global_atomic_add_f32 v[166:167], v246, off offset:128
	s_mov_b64 exec, -1
	s_mov_b64 vcc, 0x8000
	s_nop 0
	v_lshl_add_u64 v[164:165], v[164:165], 0, vcc
	s_waitcnt vmcnt(18)
	v_lshlrev_b32_e32 v168, 16, v204
	v_and_b32_e32 v169, 0xffff0000, v204
	v_lshlrev_b32_e32 v170, 16, v205
	v_and_b32_e32 v171, 0xffff0000, v205
	v_lshlrev_b32_e32 v172, 16, v206
	v_and_b32_e32 v173, 0xffff0000, v206
	v_lshlrev_b32_e32 v174, 16, v207
	v_and_b32_e32 v175, 0xffff0000, v207
	v_pk_fma_f32 v[168:169], v[76:77], 0.5, v[168:169] op_sel_hi:[1,0,1]
	v_pk_fma_f32 v[170:171], v[78:79], 0.5, v[170:171] op_sel_hi:[1,0,1]
	v_pk_fma_f32 v[172:173], v[72:73], 0.5, v[172:173] op_sel_hi:[1,0,1]
	v_pk_fma_f32 v[174:175], v[74:75], 0.5, v[174:175] op_sel_hi:[1,0,1]
	v_pk_mul_f32 v[244:245], v[168:169], v[168:169]
	v_pk_fma_f32 v[244:245], v[170:171], v[170:171], v[244:245]
	v_pk_fma_f32 v[244:245], v[172:173], v[172:173], v[244:245]
	v_pk_fma_f32 v[244:245], v[174:175], v[174:175], v[244:245]
	v_cvt_pk_bf16_f32 v204, v168, v169
	v_cvt_pk_bf16_f32 v205, v170, v171
	v_cvt_pk_bf16_f32 v206, v172, v173
	v_cvt_pk_bf16_f32 v207, v174, v175
	global_store_dwordx4 v[164:165], v[204:207], off
	v_lshlrev_b32_e32 v168, 16, v208
	v_and_b32_e32 v169, 0xffff0000, v208
	v_lshlrev_b32_e32 v170, 16, v209
	v_and_b32_e32 v171, 0xffff0000, v209
	v_lshlrev_b32_e32 v172, 16, v210
	v_and_b32_e32 v173, 0xffff0000, v210
	v_lshlrev_b32_e32 v174, 16, v211
	v_and_b32_e32 v175, 0xffff0000, v211
	v_pk_fma_f32 v[168:169], v[68:69], 0.5, v[168:169] op_sel_hi:[1,0,1]
	v_pk_fma_f32 v[170:171], v[70:71], 0.5, v[170:171] op_sel_hi:[1,0,1]
	v_pk_fma_f32 v[172:173], v[64:65], 0.5, v[172:173] op_sel_hi:[1,0,1]
	v_pk_fma_f32 v[174:175], v[66:67], 0.5, v[174:175] op_sel_hi:[1,0,1]
	v_pk_fma_f32 v[244:245], v[168:169], v[168:169], v[244:245]
	v_pk_fma_f32 v[244:245], v[170:171], v[170:171], v[244:245]
	v_pk_fma_f32 v[244:245], v[172:173], v[172:173], v[244:245]
	v_pk_fma_f32 v[244:245], v[174:175], v[174:175], v[244:245]
	v_cvt_pk_bf16_f32 v208, v168, v169
	v_cvt_pk_bf16_f32 v209, v170, v171
	v_cvt_pk_bf16_f32 v210, v172, v173
	v_cvt_pk_bf16_f32 v211, v174, v175
	global_store_dwordx4 v[164:165], v[208:211], off offset:256
	v_add_f32_e32 v246, v244, v245
	v_mov_b32_e32 v247, v246
	s_nop 1
	v_permlane32_swap_b32 v247, v246
	s_nop 1
	v_add_f32_e32 v246, v246, v247
	v_mov_b32_e32 v247, v246
	s_nop 1
	v_permlane16_swap_b32 v247, v246
	s_nop 1
	v_add_f32_e32 v246, v246, v247
	s_mov_b64 exec, s[46:47]
	global_atomic_add_f32 v[166:167], v246, off offset:192
	s_mov_b64 exec, -1
	s_mov_b64 vcc, 0x28000
	s_nop 0
	v_lshl_add_u64 v[164:165], v[164:165], 0, vcc
	s_waitcnt vmcnt(19)
	v_lshlrev_b32_e32 v168, 16, v212
	v_and_b32_e32 v169, 0xffff0000, v212
	v_lshlrev_b32_e32 v170, 16, v213
	v_and_b32_e32 v171, 0xffff0000, v213
	v_lshlrev_b32_e32 v172, 16, v214
	v_and_b32_e32 v173, 0xffff0000, v214
	v_lshlrev_b32_e32 v174, 16, v215
	v_and_b32_e32 v175, 0xffff0000, v215
	v_pk_fma_f32 v[168:169], v[60:61], 0.5, v[168:169] op_sel_hi:[1,0,1]
	v_pk_fma_f32 v[170:171], v[62:63], 0.5, v[170:171] op_sel_hi:[1,0,1]
	v_pk_fma_f32 v[172:173], v[56:57], 0.5, v[172:173] op_sel_hi:[1,0,1]
	v_pk_fma_f32 v[174:175], v[58:59], 0.5, v[174:175] op_sel_hi:[1,0,1]
	v_pk_mul_f32 v[244:245], v[168:169], v[168:169]
	v_pk_fma_f32 v[244:245], v[170:171], v[170:171], v[244:245]
	v_pk_fma_f32 v[244:245], v[172:173], v[172:173], v[244:245]
	v_pk_fma_f32 v[244:245], v[174:175], v[174:175], v[244:245]
	v_cvt_pk_bf16_f32 v212, v168, v169
	v_cvt_pk_bf16_f32 v213, v170, v171
	v_cvt_pk_bf16_f32 v214, v172, v173
	v_cvt_pk_bf16_f32 v215, v174, v175
	global_store_dwordx4 v[164:165], v[212:215], off
	v_lshlrev_b32_e32 v168, 16, v216
	v_and_b32_e32 v169, 0xffff0000, v216
	v_lshlrev_b32_e32 v170, 16, v217
	v_and_b32_e32 v171, 0xffff0000, v217
	v_lshlrev_b32_e32 v172, 16, v218
	v_and_b32_e32 v173, 0xffff0000, v218
	v_lshlrev_b32_e32 v174, 16, v219
	v_and_b32_e32 v175, 0xffff0000, v219
	v_pk_fma_f32 v[168:169], v[52:53], 0.5, v[168:169] op_sel_hi:[1,0,1]
	v_pk_fma_f32 v[170:171], v[54:55], 0.5, v[170:171] op_sel_hi:[1,0,1]
	v_pk_fma_f32 v[172:173], v[48:49], 0.5, v[172:173] op_sel_hi:[1,0,1]
	v_pk_fma_f32 v[174:175], v[50:51], 0.5, v[174:175] op_sel_hi:[1,0,1]
	v_pk_fma_f32 v[244:245], v[168:169], v[168:169], v[244:245]
	v_pk_fma_f32 v[244:245], v[170:171], v[170:171], v[244:245]
	v_pk_fma_f32 v[244:245], v[172:173], v[172:173], v[244:245]
	v_pk_fma_f32 v[244:245], v[174:175], v[174:175], v[244:245]
	v_cvt_pk_bf16_f32 v216, v168, v169
	v_cvt_pk_bf16_f32 v217, v170, v171
	v_cvt_pk_bf16_f32 v218, v172, v173
	v_cvt_pk_bf16_f32 v219, v174, v175
	global_store_dwordx4 v[164:165], v[216:219], off offset:256
	v_add_f32_e32 v246, v244, v245
	v_mov_b32_e32 v247, v246
	s_nop 1
	v_permlane32_swap_b32 v247, v246
	s_nop 1
	v_add_f32_e32 v246, v246, v247
	v_mov_b32_e32 v247, v246
	s_nop 1
	v_permlane16_swap_b32 v247, v246
	s_nop 1
	v_add_f32_e32 v246, v246, v247
	s_mov_b64 exec, s[46:47]
	global_atomic_add_f32 v[166:167], v246, off offset:512
	s_mov_b64 exec, -1
	s_mov_b64 vcc, 0x8000
	s_nop 0
	v_lshl_add_u64 v[164:165], v[164:165], 0, vcc
	s_waitcnt vmcnt(20)
	v_lshlrev_b32_e32 v168, 16, v220
	v_and_b32_e32 v169, 0xffff0000, v220
	v_lshlrev_b32_e32 v170, 16, v221
	v_and_b32_e32 v171, 0xffff0000, v221
	v_lshlrev_b32_e32 v172, 16, v222
	v_and_b32_e32 v173, 0xffff0000, v222
	v_lshlrev_b32_e32 v174, 16, v223
	v_and_b32_e32 v175, 0xffff0000, v223
	v_pk_fma_f32 v[168:169], v[44:45], 0.5, v[168:169] op_sel_hi:[1,0,1]
	v_pk_fma_f32 v[170:171], v[46:47], 0.5, v[170:171] op_sel_hi:[1,0,1]
	v_pk_fma_f32 v[172:173], v[40:41], 0.5, v[172:173] op_sel_hi:[1,0,1]
	v_pk_fma_f32 v[174:175], v[42:43], 0.5, v[174:175] op_sel_hi:[1,0,1]
	v_pk_mul_f32 v[244:245], v[168:169], v[168:169]
	v_pk_fma_f32 v[244:245], v[170:171], v[170:171], v[244:245]
	v_pk_fma_f32 v[244:245], v[172:173], v[172:173], v[244:245]
	v_pk_fma_f32 v[244:245], v[174:175], v[174:175], v[244:245]
	v_cvt_pk_bf16_f32 v220, v168, v169
	v_cvt_pk_bf16_f32 v221, v170, v171
	v_cvt_pk_bf16_f32 v222, v172, v173
	v_cvt_pk_bf16_f32 v223, v174, v175
	global_store_dwordx4 v[164:165], v[220:223], off
	v_lshlrev_b32_e32 v168, 16, v224
	v_and_b32_e32 v169, 0xffff0000, v224
	v_lshlrev_b32_e32 v170, 16, v225
	v_and_b32_e32 v171, 0xffff0000, v225
	v_lshlrev_b32_e32 v172, 16, v226
	v_and_b32_e32 v173, 0xffff0000, v226
	v_lshlrev_b32_e32 v174, 16, v227
	v_and_b32_e32 v175, 0xffff0000, v227
	v_pk_fma_f32 v[168:169], v[36:37], 0.5, v[168:169] op_sel_hi:[1,0,1]
	v_pk_fma_f32 v[170:171], v[38:39], 0.5, v[170:171] op_sel_hi:[1,0,1]
	v_pk_fma_f32 v[172:173], v[32:33], 0.5, v[172:173] op_sel_hi:[1,0,1]
	v_pk_fma_f32 v[174:175], v[34:35], 0.5, v[174:175] op_sel_hi:[1,0,1]
	v_pk_fma_f32 v[244:245], v[168:169], v[168:169], v[244:245]
	v_pk_fma_f32 v[244:245], v[170:171], v[170:171], v[244:245]
	v_pk_fma_f32 v[244:245], v[172:173], v[172:173], v[244:245]
	v_pk_fma_f32 v[244:245], v[174:175], v[174:175], v[244:245]
	v_cvt_pk_bf16_f32 v224, v168, v169
	v_cvt_pk_bf16_f32 v225, v170, v171
	v_cvt_pk_bf16_f32 v226, v172, v173
	v_cvt_pk_bf16_f32 v227, v174, v175
	global_store_dwordx4 v[164:165], v[224:227], off offset:256
	v_add_f32_e32 v246, v244, v245
	v_mov_b32_e32 v247, v246
	s_nop 1
	v_permlane32_swap_b32 v247, v246
	s_nop 1
	v_add_f32_e32 v246, v246, v247
	v_mov_b32_e32 v247, v246
	s_nop 1
	v_permlane16_swap_b32 v247, v246
	s_nop 1
	v_add_f32_e32 v246, v246, v247
	s_mov_b64 exec, s[46:47]
	global_atomic_add_f32 v[166:167], v246, off offset:576
	s_mov_b64 exec, -1
	s_mov_b64 vcc, 0x8000
	s_nop 0
	v_lshl_add_u64 v[164:165], v[164:165], 0, vcc
	s_waitcnt vmcnt(21)
	v_lshlrev_b32_e32 v168, 16, v228
	v_and_b32_e32 v169, 0xffff0000, v228
	v_lshlrev_b32_e32 v170, 16, v229
	v_and_b32_e32 v171, 0xffff0000, v229
	v_lshlrev_b32_e32 v172, 16, v230
	v_and_b32_e32 v173, 0xffff0000, v230
	v_lshlrev_b32_e32 v174, 16, v231
	v_and_b32_e32 v175, 0xffff0000, v231
	v_pk_fma_f32 v[168:169], v[28:29], 0.5, v[168:169] op_sel_hi:[1,0,1]
	v_pk_fma_f32 v[170:171], v[30:31], 0.5, v[170:171] op_sel_hi:[1,0,1]
	v_pk_fma_f32 v[172:173], v[24:25], 0.5, v[172:173] op_sel_hi:[1,0,1]
	v_pk_fma_f32 v[174:175], v[26:27], 0.5, v[174:175] op_sel_hi:[1,0,1]
	v_pk_mul_f32 v[244:245], v[168:169], v[168:169]
	v_pk_fma_f32 v[244:245], v[170:171], v[170:171], v[244:245]
	v_pk_fma_f32 v[244:245], v[172:173], v[172:173], v[244:245]
	v_pk_fma_f32 v[244:245], v[174:175], v[174:175], v[244:245]
	v_cvt_pk_bf16_f32 v228, v168, v169
	v_cvt_pk_bf16_f32 v229, v170, v171
	v_cvt_pk_bf16_f32 v230, v172, v173
	v_cvt_pk_bf16_f32 v231, v174, v175
	global_store_dwordx4 v[164:165], v[228:231], off
	v_lshlrev_b32_e32 v168, 16, v232
	v_and_b32_e32 v169, 0xffff0000, v232
	v_lshlrev_b32_e32 v170, 16, v233
	v_and_b32_e32 v171, 0xffff0000, v233
	v_lshlrev_b32_e32 v172, 16, v234
	v_and_b32_e32 v173, 0xffff0000, v234
	v_lshlrev_b32_e32 v174, 16, v235
	v_and_b32_e32 v175, 0xffff0000, v235
	v_pk_fma_f32 v[168:169], v[20:21], 0.5, v[168:169] op_sel_hi:[1,0,1]
	v_pk_fma_f32 v[170:171], v[22:23], 0.5, v[170:171] op_sel_hi:[1,0,1]
	v_pk_fma_f32 v[172:173], v[16:17], 0.5, v[172:173] op_sel_hi:[1,0,1]
	v_pk_fma_f32 v[174:175], v[18:19], 0.5, v[174:175] op_sel_hi:[1,0,1]
	v_pk_fma_f32 v[244:245], v[168:169], v[168:169], v[244:245]
	v_pk_fma_f32 v[244:245], v[170:171], v[170:171], v[244:245]
	v_pk_fma_f32 v[244:245], v[172:173], v[172:173], v[244:245]
	v_pk_fma_f32 v[244:245], v[174:175], v[174:175], v[244:245]
	v_cvt_pk_bf16_f32 v232, v168, v169
	v_cvt_pk_bf16_f32 v233, v170, v171
	v_cvt_pk_bf16_f32 v234, v172, v173
	v_cvt_pk_bf16_f32 v235, v174, v175
	global_store_dwordx4 v[164:165], v[232:235], off offset:256
	v_add_f32_e32 v246, v244, v245
	v_mov_b32_e32 v247, v246
	s_nop 1
	v_permlane32_swap_b32 v247, v246
	s_nop 1
	v_add_f32_e32 v246, v246, v247
	v_mov_b32_e32 v247, v246
	s_nop 1
	v_permlane16_swap_b32 v247, v246
	s_nop 1
	v_add_f32_e32 v246, v246, v247
	s_mov_b64 exec, s[46:47]
	global_atomic_add_f32 v[166:167], v246, off offset:640
	s_mov_b64 exec, -1
	s_mov_b64 vcc, 0x8000
	s_nop 0
	v_lshl_add_u64 v[164:165], v[164:165], 0, vcc
	s_waitcnt vmcnt(22)
	v_lshlrev_b32_e32 v168, 16, v236
	v_and_b32_e32 v169, 0xffff0000, v236
	v_lshlrev_b32_e32 v170, 16, v237
	v_and_b32_e32 v171, 0xffff0000, v237
	v_lshlrev_b32_e32 v172, 16, v238
	v_and_b32_e32 v173, 0xffff0000, v238
	v_lshlrev_b32_e32 v174, 16, v239
	v_and_b32_e32 v175, 0xffff0000, v239
	v_pk_fma_f32 v[168:169], v[12:13], 0.5, v[168:169] op_sel_hi:[1,0,1]
	v_pk_fma_f32 v[170:171], v[14:15], 0.5, v[170:171] op_sel_hi:[1,0,1]
	v_pk_fma_f32 v[172:173], v[8:9], 0.5, v[172:173] op_sel_hi:[1,0,1]
	v_pk_fma_f32 v[174:175], v[10:11], 0.5, v[174:175] op_sel_hi:[1,0,1]
	v_pk_mul_f32 v[244:245], v[168:169], v[168:169]
	v_pk_fma_f32 v[244:245], v[170:171], v[170:171], v[244:245]
	v_pk_fma_f32 v[244:245], v[172:173], v[172:173], v[244:245]
	v_pk_fma_f32 v[244:245], v[174:175], v[174:175], v[244:245]
	v_cvt_pk_bf16_f32 v236, v168, v169
	v_cvt_pk_bf16_f32 v237, v170, v171
	v_cvt_pk_bf16_f32 v238, v172, v173
	v_cvt_pk_bf16_f32 v239, v174, v175
	global_store_dwordx4 v[164:165], v[236:239], off
	v_lshlrev_b32_e32 v168, 16, v240
	v_and_b32_e32 v169, 0xffff0000, v240
	v_lshlrev_b32_e32 v170, 16, v241
	v_and_b32_e32 v171, 0xffff0000, v241
	v_lshlrev_b32_e32 v172, 16, v242
	v_and_b32_e32 v173, 0xffff0000, v242
	v_lshlrev_b32_e32 v174, 16, v243
	v_and_b32_e32 v175, 0xffff0000, v243
	v_pk_fma_f32 v[168:169], v[4:5], 0.5, v[168:169] op_sel_hi:[1,0,1]
	v_pk_fma_f32 v[170:171], v[6:7], 0.5, v[170:171] op_sel_hi:[1,0,1]
	v_pk_fma_f32 v[172:173], v[0:1], 0.5, v[172:173] op_sel_hi:[1,0,1]
	v_pk_fma_f32 v[174:175], v[2:3], 0.5, v[174:175] op_sel_hi:[1,0,1]
	v_pk_fma_f32 v[244:245], v[168:169], v[168:169], v[244:245]
	v_pk_fma_f32 v[244:245], v[170:171], v[170:171], v[244:245]
	v_pk_fma_f32 v[244:245], v[172:173], v[172:173], v[244:245]
	v_pk_fma_f32 v[244:245], v[174:175], v[174:175], v[244:245]
	v_cvt_pk_bf16_f32 v240, v168, v169
	v_cvt_pk_bf16_f32 v241, v170, v171
	v_cvt_pk_bf16_f32 v242, v172, v173
	v_cvt_pk_bf16_f32 v243, v174, v175
	global_store_dwordx4 v[164:165], v[240:243], off offset:256
	v_add_f32_e32 v246, v244, v245
	v_mov_b32_e32 v247, v246
	s_nop 1
	v_permlane32_swap_b32 v247, v246
	s_nop 1
	v_add_f32_e32 v246, v246, v247
	v_mov_b32_e32 v247, v246
	s_nop 1
	v_permlane16_swap_b32 v247, v246
	s_nop 1
	v_add_f32_e32 v246, v246, v247
	s_mov_b64 exec, s[46:47]
	global_atomic_add_f32 v[166:167], v246, off offset:704
	s_mov_b64 exec, -1
	s_mov_b64 s[42:43], exec
	s_branch .LBB0_659
